# attention unit chain: queue ticket atomic prefetched after first row of output stores and consumed with counted vmcnt(60); first-tile QK no longer waits vmcnt(7..0) for long-loaded Q registers
# speedup vs baseline: 1.0043x; 1.0043x over previous
.LBB0_5:
	s_or_b64 exec, exec, s[4:5]
	s_cmp_ge_i32 s30, s31
	s_cbranch_scc1 .LBB0_1287
	s_add_u32 s88, s28, 0xd000000
	s_addc_u32 s89, s29, 0
	s_add_u32 s90, s28, 0x1000000
	s_addc_u32 s91, s29, 0
	s_add_u32 s66, s28, 0x3000000
	s_addc_u32 s67, s29, 0
	s_add_u32 s95, s28, 0x5000000
	s_addc_u32 s55, s29, 0
	s_add_u32 s4, s28, 0x900000
	v_writelane_b32 v253, s4, 8
	s_addc_u32 s4, s29, 0
	s_add_u32 s6, s28, 0x37000000
	v_writelane_b32 v253, s4, 9
	s_addc_u32 s7, s29, 0
	v_writelane_b32 v253, s6, 10
	s_mul_i32 s4, s85, s84
	v_lshrrev_b32_e32 v1, 20, v0
	v_writelane_b32 v253, s7, 11
	s_add_u32 s6, s28, 0x3d000000
	s_addc_u32 s7, s29, 0
	s_lshl_b32 s57, s94, 3
	s_lshl_b32 s92, s84, 3
	s_add_u32 s85, s28, 0x8000000
	v_writelane_b32 v253, s6, 12
	s_addc_u32 s13, s29, 0
	s_add_u32 s5, s28, 0x200000
	v_writelane_b32 v253, s7, 13
	v_writelane_b32 v253, s5, 14
	s_addc_u32 s5, s29, 0
	s_add_u32 s6, s28, 0x22000000
	v_writelane_b32 v253, s5, 15
	s_addc_u32 s7, s29, 0
	v_writelane_b32 v253, s6, 16
	v_lshrrev_b32_e32 v0, 10, v0
	v_or_b32_e32 v0, v0, v1
	v_writelane_b32 v253, s7, 17
	s_add_u32 s6, s28, 0x3a000000
	s_addc_u32 s7, s29, 0
	v_writelane_b32 v253, s6, 18
	s_load_dwordx16 s[68:83], s[0:1], 0x0
	v_writelane_b32 v255, 0, 62
	s_mul_i32 s16, s84, 0xc000
	v_writelane_b32 v253, s7, 19
	s_add_u32 s6, s28, 0x500000
	s_addc_u32 s7, s29, 0
	v_writelane_b32 v253, s6, 20
	s_add_u32 s5, s28, 0x300000
	s_mul_hi_i32 s17, s92, 0x1800
	v_writelane_b32 v253, s7, 21
	v_writelane_b32 v253, s5, 22
	s_addc_u32 s5, s29, 0
	v_writelane_b32 v253, s5, 23
	s_add_u32 s5, s28, 0x3c000000
	v_writelane_b32 v253, s5, 24
	s_addc_u32 s5, s29, 0
	s_add_u32 s6, s28, 0x100000
	v_writelane_b32 v253, s5, 25
	s_addc_u32 s7, s29, 0
	v_writelane_b32 v253, s6, 26
	s_cmp_gt_i32 s30, -1
	s_load_dword s5, s[0:1], 0x88
	v_writelane_b32 v253, s7, 27
	s_cselect_b64 s[6:7], -1, 0
	v_writelane_b32 v253, s6, 28
	s_mul_i32 s18, s84, 0x52000
	s_waitcnt lgkmcnt(0)
	s_mul_i32 s5, s4, s5
	v_writelane_b32 v253, s7, 29
	s_add_u32 s6, s28, 0x1200
	s_addc_u32 s7, s29, 0
	v_writelane_b32 v253, s6, 30
	s_mul_hi_i32 s19, s92, 0xa400
	s_mul_i32 s20, s84, 0x14000
	v_writelane_b32 v253, s7, 31
	s_add_u32 s6, s28, 0x1400
	s_addc_u32 s7, s29, 0
	v_writelane_b32 v253, s6, 32
	s_mul_hi_i32 s21, s92, 0x2800
	v_mov_b32_e32 v1, 0
	v_writelane_b32 v253, s7, 33
	s_add_u32 s6, s28, 0x1500
	s_addc_u32 s7, s29, 0
	v_writelane_b32 v253, s6, 34
	v_mov_b32_e32 v250, 0x358637bd
	v_mov_b32_e32 v251, 0x7f800000
	v_writelane_b32 v253, s7, 35
	s_add_u32 s6, s28, 0x1600
	s_addc_u32 s7, s29, 0
	v_writelane_b32 v253, s6, 36
	v_mov_b32_e32 v16, 0xff800000
	s_mov_b32 s33, 0x3fb8aa3b
	v_writelane_b32 v253, s7, 37
	s_add_u32 s6, s28, 0x1700
	s_addc_u32 s7, s29, 0
	v_writelane_b32 v253, s6, 38
	s_mov_b32 s12, 0xc2ce8ed0
	s_mov_b32 s15, 0x42b17218
	v_writelane_b32 v253, s7, 39
	s_add_u32 s6, s28, 0x1800
	s_addc_u32 s7, s29, 0
	v_writelane_b32 v253, s6, 40
	s_mov_b32 s34, 0x41000000
	s_mov_b32 s87, 0
	v_writelane_b32 v253, s7, 41
	s_add_u32 s6, s28, 0x1900
	s_addc_u32 s7, s29, 0
	v_writelane_b32 v253, s6, 42
	s_mov_b64 s[36:37], 0x80
	s_mov_b32 s14, 0x3e0293ee
	v_writelane_b32 v253, s7, 43
	s_add_u32 s6, s28, 0x1a00
	s_addc_u32 s7, s29, 0
	v_writelane_b32 v253, s6, 44
	s_nop 1
	v_writelane_b32 v253, s7, 45
	s_add_u32 s6, s28, 0x1b00
	s_addc_u32 s7, s29, 0
	v_writelane_b32 v253, s6, 46
	s_nop 1
	v_writelane_b32 v253, s7, 47
	s_add_u32 s6, s28, 0x1c00
	s_addc_u32 s7, s29, 0
	v_writelane_b32 v253, s6, 48
	s_nop 1
	v_writelane_b32 v253, s7, 49
	s_add_u32 s6, s28, 0x1d00
	s_addc_u32 s7, s29, 0
	v_writelane_b32 v253, s6, 50
	s_nop 1
	v_writelane_b32 v253, s7, 51
	s_add_u32 s6, s28, 0x1e00
	s_addc_u32 s7, s29, 0
	v_writelane_b32 v253, s6, 52
	s_nop 1
	v_writelane_b32 v253, s7, 53
	s_add_u32 s6, s28, 0x1f00
	s_addc_u32 s7, s29, 0
	v_writelane_b32 v253, s6, 54
	s_nop 1
	v_writelane_b32 v253, s7, 55
	s_add_u32 s6, s28, 0x2000
	s_addc_u32 s7, s29, 0
	v_writelane_b32 v253, s6, 56
	s_nop 1
	v_writelane_b32 v253, s7, 57
	s_add_u32 s6, s28, 0x2100
	s_addc_u32 s7, s29, 0
	v_writelane_b32 v253, s6, 58
	s_nop 1
	v_writelane_b32 v253, s7, 59
	s_add_u32 s6, s28, 0x2200
	s_addc_u32 s7, s29, 0
	v_writelane_b32 v253, s6, 60
	s_nop 1
	v_writelane_b32 v253, s7, 61
	s_add_u32 s6, s28, 0x2300
	s_addc_u32 s7, s29, 0
	v_writelane_b32 v253, s6, 62
	s_cmp_eq_u32 s8, 15
	s_nop 0
	v_writelane_b32 v253, s7, 63
	s_cselect_b64 s[6:7], -1, 0
	v_writelane_b32 v254, s6, 0
	s_cmp_eq_u32 s8, 14
	s_nop 0
	v_writelane_b32 v254, s7, 1
	s_cselect_b64 s[6:7], -1, 0
	v_writelane_b32 v254, s6, 2
	s_cmp_eq_u32 s8, 13
	s_nop 0
	v_writelane_b32 v254, s7, 3
	s_cselect_b64 s[6:7], -1, 0
	v_writelane_b32 v254, s6, 4
	s_cmp_eq_u32 s8, 12
	s_nop 0
	v_writelane_b32 v254, s7, 5
	s_cselect_b64 s[6:7], -1, 0
	v_writelane_b32 v254, s6, 6
	s_cmp_eq_u32 s8, 11
	s_nop 0
	v_writelane_b32 v254, s7, 7
	s_cselect_b64 s[6:7], -1, 0
	v_writelane_b32 v254, s6, 8
	s_cmp_eq_u32 s8, 10
	s_nop 0
	v_writelane_b32 v254, s7, 9
	s_cselect_b64 s[6:7], -1, 0
	v_writelane_b32 v254, s6, 10
	s_cmp_eq_u32 s8, 9
	s_nop 0
	v_writelane_b32 v254, s7, 11
	s_cselect_b64 s[6:7], -1, 0
	v_writelane_b32 v254, s6, 12
	s_cmp_eq_u32 s8, 8
	s_nop 0
	v_writelane_b32 v254, s7, 13
	s_cselect_b64 s[6:7], -1, 0
	v_writelane_b32 v254, s6, 14
	s_cmp_eq_u32 s8, 7
	s_nop 0
	v_writelane_b32 v254, s7, 15
	s_cselect_b64 s[6:7], -1, 0
	v_writelane_b32 v254, s6, 16
	s_cmp_eq_u32 s8, 6
	s_nop 0
	v_writelane_b32 v254, s7, 17
	s_cselect_b64 s[6:7], -1, 0
	v_writelane_b32 v254, s6, 18
	s_cmp_eq_u32 s8, 5
	s_nop 0
	v_writelane_b32 v254, s7, 19
	s_cselect_b64 s[6:7], -1, 0
	v_writelane_b32 v254, s6, 20
	s_cmp_eq_u32 s8, 4
	s_nop 0
	v_writelane_b32 v254, s7, 21
	s_cselect_b64 s[6:7], -1, 0
	v_writelane_b32 v254, s6, 22
	s_cmp_eq_u32 s8, 3
	s_nop 0
	v_writelane_b32 v254, s7, 23
	s_cselect_b64 s[6:7], -1, 0
	v_writelane_b32 v254, s6, 24
	s_cmp_eq_u32 s8, 2
	s_nop 0
	v_writelane_b32 v254, s7, 25
	s_cselect_b64 s[6:7], -1, 0
	v_writelane_b32 v254, s6, 26
	s_cmp_eq_u32 s8, 1
	s_nop 0
	v_writelane_b32 v254, s7, 27
	s_cselect_b64 s[6:7], -1, 0
	v_writelane_b32 v254, s6, 28
	s_cmp_eq_u32 s8, 0
	s_nop 0
	v_writelane_b32 v254, s7, 29
	s_cselect_b64 s[6:7], -1, 0
	s_lshl_b32 s4, s8, 8
	s_add_u32 s2, s2, s4
	v_writelane_b32 v254, s6, 30
	s_addc_u32 s3, s3, 0
	s_nop 0
	v_writelane_b32 v254, s7, 31
	s_add_u32 s6, s2, 0x1400
	s_addc_u32 s7, s3, 0
	v_writelane_b32 v254, s6, 32
	s_add_u32 s2, s2, 0x2400
	s_addc_u32 s3, s3, 0
	v_writelane_b32 v254, s7, 33
	v_writelane_b32 v254, s2, 34
	s_nop 1
	v_writelane_b32 v254, s3, 35
	s_movk_i32 s2, 0x3ff
	v_and_or_b32 v0, v0, s2, v252
	s_add_u32 s2, s28, 0x4400
	s_addc_u32 s3, s29, 0
	v_writelane_b32 v254, s2, 36
	s_nop 1
	v_writelane_b32 v254, s3, 37
	s_add_u32 s2, s28, 0x4500
	s_addc_u32 s3, s29, 0
	v_writelane_b32 v254, s2, 38
	s_ashr_i32 s93, s92, 31
	s_lshl_b64 s[6:7], s[92:93], 5
	v_writelane_b32 v254, s3, 39
	s_lshl_b64 s[2:3], s[92:93], 4
	v_writelane_b32 v254, s6, 40
	s_add_u32 s0, s68, 0x1000
	s_nop 0
	v_writelane_b32 v254, s7, 41
	v_writelane_b32 v254, s0, 42
	s_addc_u32 s0, s69, 0
	v_writelane_b32 v254, s0, 43
	s_lshl_b64 s[6:7], s[92:93], 12
	s_lshl_b64 s[0:1], s[92:93], 13
	v_writelane_b32 v254, s6, 44
	s_add_u32 s4, s70, 0x1000
	s_mov_b32 s93, s5
	v_writelane_b32 v254, s7, 45
	v_writelane_b32 v254, s4, 46
	v_writelane_b32 v254, s68, 47
	s_nop 1
	v_writelane_b32 v254, s69, 48
	v_writelane_b32 v254, s70, 49
	v_writelane_b32 v254, s71, 50
	v_writelane_b32 v254, s72, 51
	v_writelane_b32 v254, s73, 52
	v_writelane_b32 v254, s74, 53
	v_writelane_b32 v254, s75, 54
	v_writelane_b32 v254, s76, 55
	v_writelane_b32 v254, s77, 56
	v_writelane_b32 v254, s78, 57
	v_writelane_b32 v254, s79, 58
	v_writelane_b32 v254, s80, 59
	v_writelane_b32 v254, s81, 60
	v_writelane_b32 v254, s82, 61
	v_writelane_b32 v254, s83, 62
	s_mov_b64 s[80:81], s[0:1]
	s_addc_u32 s0, s71, 0
	v_writelane_b32 v254, s0, 63
	s_add_i32 s0, 0, 0x22100
	v_writelane_b32 v255, s0, 0
	s_add_i32 s0, 0, 0x20000
	v_writelane_b32 v255, s0, 1
	s_add_i32 s0, 0, 0x22080
	v_writelane_b32 v255, s0, 2
	s_add_i32 s0, 0, 0x22040
	v_writelane_b32 v255, s0, 3
	s_add_i32 s0, 0, 0x22044
	v_writelane_b32 v255, s0, 4
	v_cmp_eq_u32_e64 s[0:1], 0, v0
	s_mov_b64 s[74:75], s[30:31]
	s_mov_b64 s[72:73], s[28:29]
	v_writelane_b32 v255, s0, 5
	s_mov_b64 s[70:71], s[26:27]
	s_mov_b64 s[68:69], s[24:25]
	v_writelane_b32 v255, s1, 6
	v_writelane_b32 v255, s94, 7
	v_writelane_b32 v255, s66, 8
	s_mov_b32 s0, s92
	s_mov_b32 s28, 0x800000
	v_writelane_b32 v255, s67, 9
	v_writelane_b32 v255, s95, 10
	v_writelane_b32 v255, s55, 11
	v_writelane_b32 v255, s57, 12
	v_writelane_b32 v255, s0, 13
	s_add_i32 s30, 0, 0x22000
	s_mov_b32 s31, 0x4e6e6b28
	v_writelane_b32 v255, s1, 14
	v_writelane_b32 v255, s93, 15
	v_writelane_b32 v255, s16, 16
	s_nop 1
	v_writelane_b32 v255, s17, 17
	v_writelane_b32 v255, s18, 18
	s_nop 1
	v_writelane_b32 v255, s19, 19
	v_writelane_b32 v255, s20, 20
	s_nop 1
	v_writelane_b32 v255, s21, 21
	v_writelane_b32 v255, s48, 22
	s_nop 1
	v_writelane_b32 v255, s49, 23
	v_writelane_b32 v255, s80, 24
	s_nop 1
	v_writelane_b32 v255, s81, 25
	v_writelane_b32 v255, s2, 26
	s_nop 1
	v_writelane_b32 v255, s3, 27
	s_branch .LBB0_11

.LBB0_506:
	s_and_saveexec_b64 s[0:1], s[96:97]
	s_cbranch_execz .LBB0_510
	s_mov_b64 s[22:23], exec
	v_mbcnt_lo_u32_b32 v0, s22, 0
	v_mbcnt_hi_u32_b32 v0, s23, v0
	v_cmp_eq_u32_e32 vcc, 0, v0
	s_and_saveexec_b64 s[24:25], vcc
	s_cbranch_execz .LBB0_509
	v_readlane_b32 s8, v255, 62
	s_nop 0
	s_cmp_lg_u32 s8, 0
	s_cbranch_scc1 .Lq_have
	s_bcnt1_i32_b64 s8, s[22:23]
	v_mov_b32_e32 v14, s8
	global_atomic_add v14, v1, v14, s[2:3] sc0
	s_waitcnt vmcnt(0)
	s_branch .LBB0_509
.Lq_have:
	s_waitcnt vmcnt(60)
	v_mov_b32_e32 v14, v25
.LBB0_509:
	s_or_b64 exec, exec, s[24:25]
	s_load_dword s8, s[48:49], 0x10
	s_waitcnt lgkmcnt(0)
	s_lshr_b32 s8, s8, 16
	s_and_b32 s8, 0xffff, s8
	s_cmp_lg_u32 s8, 0
	s_cselect_b64 s[22:23], -1, 0
	v_readfirstlane_b32 s8, v14
	s_cmp_lg_u64 s[22:23], 0
	s_addc_u32 s8, s8, s84
	v_add_u32_e32 v0, s8, v0
	v_mov_b32_e32 v14, s30
	ds_write_b32 v14, v0
.LBB0_510:
	s_or_b64 exec, exec, s[0:1]
	v_writelane_b32 v255, 0, 62
	v_mov_b32_e32 v0, s30
	s_waitcnt lgkmcnt(0)
	s_barrier
	ds_read_b32 v0, v0
	s_mov_b64 s[0:1], -1
	s_mov_b32 s92, 0
	s_mov_b64 s[26:27], -1
	s_waitcnt lgkmcnt(0)
	v_readfirstlane_b32 s93, v0
	s_cmp_ge_i32 s93, s15
	s_cbranch_scc1 .LBB0_515
	s_cmp_ge_i32 s93, s33
	s_mov_b64 s[22:23], -1
	s_cbranch_scc0 .LBB0_513
	s_sub_i32 s92, s93, s12
	s_mov_b64 s[22:23], 0

.LBB0_540:
	v_bfe_u32 v228, v218, 5, 1
	v_mov_b32_e32 v17, 0x41000000
	s_ashr_i32 s0, s40, 1
	v_and_b32_e32 v219, 31, v218
	v_mul_f32_e32 v206, s61, v17
	v_mov_b32_e32 v17, 0x42000000
	s_and_b32 s52, s0, 0xffffffe0
	v_lshlrev_b32_e32 v220, 2, v228
	v_mul_f32_e32 v204, s61, v17
	s_add_i32 s58, s52, s29
	v_sub_u32_e32 v17, v219, v220
	v_add_u32_e32 v225, s58, v17
	s_add_i32 s59, s58, 31
	s_cmp_gt_i32 s41, s59
	s_cselect_b64 s[0:1], -1, 0
	s_or_b32 s29, s41, 63
	s_sub_i32 s60, s58, s53
	s_cmp_le_i32 s29, s60
	s_cselect_b64 s[78:79], -1, 0
	s_or_b64 s[0:1], s[0:1], s[78:79]
	s_and_b64 vcc, exec, s[0:1]
	s_cbranch_vccnz .LBB0_542
	v_sub_u32_e32 v17, s41, v225
	v_cvt_f32_i32_e32 v17, v17
	v_lshlrev_b32_e32 v22, 4, v228
	v_lshlrev_b32_e32 v23, 4, v219
	v_bitop3_b32 v18, v22, v23, s69 bitop3:0x78
	v_mul_f32_e32 v32, s61, v17
	v_fma_f32 v33, s61, v17, s61
	v_lshlrev_b32_e32 v17, 8, v219
	v_add3_u32 v24, 0, v18, v17
	ds_read_b128 v[18:21], v24 offset:32768
	v_add_f32_e32 v34, s61, v33
	v_add_f32_e32 v35, s61, v34
	v_pk_add_f32 v[36:37], v[206:207], v[32:33] op_sel_hi:[0,1]
	v_pk_add_f32 v[38:39], v[206:207], v[34:35] op_sel_hi:[0,1]
	v_pk_add_f32 v[40:41], v[206:207], v[36:37] op_sel_hi:[0,1]
	v_pk_add_f32 v[42:43], v[206:207], v[38:39] op_sel_hi:[0,1]
	v_pk_add_f32 v[44:45], v[206:207], v[40:41] op_sel_hi:[0,1]
	v_pk_add_f32 v[46:47], v[206:207], v[42:43] op_sel_hi:[0,1]
	v_pk_add_f32 v[48:49], v[204:205], v[32:33] op_sel_hi:[0,1]
	v_pk_add_f32 v[52:53], v[204:205], v[36:37] op_sel_hi:[0,1]
	v_pk_add_f32 v[56:57], v[204:205], v[40:41] op_sel_hi:[0,1]
	v_pk_add_f32 v[50:51], v[204:205], v[34:35] op_sel_hi:[0,1]
	v_pk_add_f32 v[60:61], v[204:205], v[44:45] op_sel_hi:[0,1]
	v_pk_add_f32 v[54:55], v[204:205], v[38:39] op_sel_hi:[0,1]
	v_pk_add_f32 v[58:59], v[204:205], v[42:43] op_sel_hi:[0,1]
	v_pk_add_f32 v[62:63], v[204:205], v[46:47] op_sel_hi:[0,1]
	s_waitcnt vmcnt(63) lgkmcnt(0)
	v_mfma_f32_32x32x16_bf16 v[32:47], v[18:21], v[188:191], v[32:47]
	ds_read_b128 v[18:21], v24 offset:40960
	v_and_b32_e32 v23, 0x70, v23
	v_bitop3_b32 v25, v22, v23, 32 bitop3:0x36
	v_add3_u32 v25, 0, v25, v17
	v_bitop3_b32 v26, v22, v23, 64 bitop3:0x36
	v_add3_u32 v26, 0, v26, v17
	v_bitop3_b32 v22, v22, v23, s68 bitop3:0x36
	s_waitcnt lgkmcnt(0)
	v_mfma_f32_32x32x16_bf16 v[48:63], v[18:21], v[188:191], v[48:63]
	ds_read_b128 v[18:21], v25 offset:32768
	v_add3_u32 v17, 0, v22, v17
	s_waitcnt lgkmcnt(0)
	v_mfma_f32_32x32x16_bf16 v[32:47], v[18:21], v[184:187], v[32:47]
	ds_read_b128 v[18:21], v25 offset:40960
	s_waitcnt lgkmcnt(0)
	v_mfma_f32_32x32x16_bf16 v[48:63], v[18:21], v[184:187], v[48:63]
	ds_read_b128 v[18:21], v26 offset:32768
	s_waitcnt lgkmcnt(0)
	v_mfma_f32_32x32x16_bf16 v[32:47], v[18:21], v[180:183], v[32:47]
	ds_read_b128 v[18:21], v26 offset:40960
	s_waitcnt lgkmcnt(0)
	v_mfma_f32_32x32x16_bf16 v[48:63], v[18:21], v[180:183], v[48:63]
	ds_read_b128 v[18:21], v17 offset:32768
	s_waitcnt lgkmcnt(0)
	v_mfma_f32_32x32x16_bf16 v[32:47], v[18:21], v[176:179], v[32:47]
	ds_read_b128 v[18:21], v17 offset:40960
	s_waitcnt lgkmcnt(0)
	v_mfma_f32_32x32x16_bf16 v[48:63], v[18:21], v[176:179], v[48:63]
	ds_read_b128 v[18:21], v24 offset:32896
	s_waitcnt lgkmcnt(0)
	v_mfma_f32_32x32x16_bf16 v[32:47], v[18:21], v[172:175], v[32:47]
	ds_read_b128 v[18:21], v24 offset:41088
	s_waitcnt lgkmcnt(0)
	v_mfma_f32_32x32x16_bf16 v[48:63], v[18:21], v[172:175], v[48:63]
	ds_read_b128 v[18:21], v25 offset:32896
	s_waitcnt lgkmcnt(0)
	v_mfma_f32_32x32x16_bf16 v[32:47], v[18:21], v[168:171], v[32:47]
	ds_read_b128 v[18:21], v25 offset:41088
	s_waitcnt lgkmcnt(0)
	v_mfma_f32_32x32x16_bf16 v[48:63], v[18:21], v[168:171], v[48:63]
	ds_read_b128 v[18:21], v26 offset:32896
	s_waitcnt lgkmcnt(0)
	v_mfma_f32_32x32x16_bf16 v[32:47], v[18:21], v[164:167], v[32:47]
	ds_read_b128 v[18:21], v26 offset:41088
	s_waitcnt lgkmcnt(0)
	v_mfma_f32_32x32x16_bf16 v[48:63], v[18:21], v[164:167], v[48:63]
	ds_read_b128 v[18:21], v17 offset:32896
	s_waitcnt lgkmcnt(0)
	v_mfma_f32_32x32x16_bf16 v[32:47], v[18:21], v[160:163], v[32:47]
	ds_read_b128 v[18:21], v17 offset:41088
	s_waitcnt lgkmcnt(0)
	v_mfma_f32_32x32x16_bf16 v[48:63], v[18:21], v[160:163], v[48:63]
	s_xor_b64 s[0:1], s[0:1], -1
	s_andn2_b64 vcc, exec, s[0:1]
	s_cbranch_vccz .LBB0_543
	s_branch .LBB0_545

.LBB0_601:
	s_or_b64 exec, exec, s[0:1]
	s_mul_i32 s0, s8, s86
	s_mul_hi_u32 s1, s52, s86
	s_add_i32 s1, s1, s0
	s_mul_i32 s0, s52, s86
	s_lshl_b64 s[0:1], s[0:1], 1
	s_add_u32 s0, s42, s0
	v_mul_lo_u32 v0, v220, s86
	s_addc_u32 s1, s43, s1
	v_or_b32_e32 v0, v0, v219
	v_and_b32_e32 v14, 1, v218
	v_cmp_eq_u32_e32 vcc, 0, v14
	v_lshl_add_u64 v[14:15], v[0:1], 1, s[0:1]
	ds_read_b32 v0, v217
	s_waitcnt lgkmcnt(0)
	v_rcp_f32_e32 v0, v0
	s_nop 0
	v_mul_f32_e32 v17, v80, v0
	v_mul_f32_e32 v18, v64, v0
	v_mul_f32_e32 v19, v48, v0
	v_mul_f32_e32 v20, v32, v0
	v_mov_b32_dpp v21, v17 quad_perm:[1,0,3,2] row_mask:0xf bank_mask:0xf bound_ctrl:1
	v_mov_b32_dpp v22, v18 quad_perm:[1,0,3,2] row_mask:0xf bank_mask:0xf bound_ctrl:1
	v_mov_b32_dpp v23, v19 quad_perm:[1,0,3,2] row_mask:0xf bank_mask:0xf bound_ctrl:1
	v_mov_b32_dpp v24, v20 quad_perm:[1,0,3,2] row_mask:0xf bank_mask:0xf bound_ctrl:1
	v_cvt_pk_bf16_f32 v17, v17, v21
	v_cvt_pk_bf16_f32 v18, v18, v22
	v_cvt_pk_bf16_f32 v19, v19, v23
	v_cvt_pk_bf16_f32 v20, v20, v24
	s_and_saveexec_b64 s[0:1], vcc
	global_store_dword v[14:15], v17, off
	global_store_dword v[14:15], v18, off offset:64
	global_store_dword v[14:15], v19, off offset:128
	global_store_dword v[14:15], v20, off offset:192
	s_or_b64 exec, exec, s[0:1]
	s_cmp_lg_u64 s[26:27], 0
	s_cbranch_scc1 .Lq_nopf
	s_and_saveexec_b64 s[0:1], s[96:97]
	s_cbranch_execz .Lq_pf_skip
	v_mov_b32_e32 v25, 1
	global_atomic_add v25, v1, v25, s[2:3] sc0
.Lq_pf_skip:
	s_or_b64 exec, exec, s[0:1]
	v_writelane_b32 v255, 1, 62
.Lq_nopf:
	ds_read_b32 v0, v217 offset:4
	v_lshl_add_u64 v[14:15], s[86:87], 1, v[14:15]
	s_waitcnt lgkmcnt(0)
	v_rcp_f32_e32 v0, v0
	s_nop 0
	v_mul_f32_e32 v17, v81, v0
	v_mul_f32_e32 v18, v65, v0
	v_mul_f32_e32 v19, v49, v0
	v_mul_f32_e32 v20, v33, v0
	v_mov_b32_dpp v21, v17 quad_perm:[1,0,3,2] row_mask:0xf bank_mask:0xf bound_ctrl:1
	v_mov_b32_dpp v22, v18 quad_perm:[1,0,3,2] row_mask:0xf bank_mask:0xf bound_ctrl:1
	v_mov_b32_dpp v23, v19 quad_perm:[1,0,3,2] row_mask:0xf bank_mask:0xf bound_ctrl:1
	v_mov_b32_dpp v24, v20 quad_perm:[1,0,3,2] row_mask:0xf bank_mask:0xf bound_ctrl:1
	v_cvt_pk_bf16_f32 v17, v17, v21
	v_cvt_pk_bf16_f32 v18, v18, v22
	v_cvt_pk_bf16_f32 v19, v19, v23
	v_cvt_pk_bf16_f32 v20, v20, v24
	s_and_saveexec_b64 s[0:1], vcc
	global_store_dword v[14:15], v17, off
	global_store_dword v[14:15], v18, off offset:64
	global_store_dword v[14:15], v19, off offset:128
	global_store_dword v[14:15], v20, off offset:192
	s_or_b64 exec, exec, s[0:1]
	ds_read_b32 v0, v217 offset:8
	s_lshl_b64 s[0:1], s[86:87], 1
	v_lshl_add_u64 v[14:15], v[14:15], 0, s[0:1]
	s_waitcnt lgkmcnt(0)
	v_rcp_f32_e32 v0, v0
	s_nop 0
	v_mul_f32_e32 v17, v82, v0
	v_mul_f32_e32 v18, v66, v0
	v_mul_f32_e32 v19, v50, v0
	v_mul_f32_e32 v20, v34, v0
	v_mov_b32_dpp v21, v17 quad_perm:[1,0,3,2] row_mask:0xf bank_mask:0xf bound_ctrl:1
	v_mov_b32_dpp v22, v18 quad_perm:[1,0,3,2] row_mask:0xf bank_mask:0xf bound_ctrl:1
	v_mov_b32_dpp v23, v19 quad_perm:[1,0,3,2] row_mask:0xf bank_mask:0xf bound_ctrl:1
	v_mov_b32_dpp v24, v20 quad_perm:[1,0,3,2] row_mask:0xf bank_mask:0xf bound_ctrl:1
	v_cvt_pk_bf16_f32 v17, v17, v21
	v_cvt_pk_bf16_f32 v18, v18, v22
	v_cvt_pk_bf16_f32 v19, v19, v23
	v_cvt_pk_bf16_f32 v20, v20, v24
	s_and_saveexec_b64 s[22:23], vcc
	global_store_dword v[14:15], v17, off
	global_store_dword v[14:15], v18, off offset:64
	global_store_dword v[14:15], v19, off offset:128
	global_store_dword v[14:15], v20, off offset:192
	s_or_b64 exec, exec, s[22:23]
	ds_read_b32 v0, v217 offset:12
	v_lshl_add_u64 v[14:15], v[14:15], 0, s[0:1]
	s_waitcnt lgkmcnt(0)
	v_rcp_f32_e32 v0, v0
	s_nop 0
	v_mul_f32_e32 v17, v83, v0
	v_mul_f32_e32 v18, v67, v0
	v_mul_f32_e32 v19, v51, v0
	v_mul_f32_e32 v20, v35, v0
	v_mov_b32_dpp v21, v17 quad_perm:[1,0,3,2] row_mask:0xf bank_mask:0xf bound_ctrl:1
	v_mov_b32_dpp v22, v18 quad_perm:[1,0,3,2] row_mask:0xf bank_mask:0xf bound_ctrl:1
	v_mov_b32_dpp v23, v19 quad_perm:[1,0,3,2] row_mask:0xf bank_mask:0xf bound_ctrl:1
	v_mov_b32_dpp v24, v20 quad_perm:[1,0,3,2] row_mask:0xf bank_mask:0xf bound_ctrl:1
	v_cvt_pk_bf16_f32 v17, v17, v21
	v_cvt_pk_bf16_f32 v18, v18, v22
	v_cvt_pk_bf16_f32 v19, v19, v23
	v_cvt_pk_bf16_f32 v20, v20, v24
	s_and_saveexec_b64 s[22:23], vcc
	global_store_dword v[14:15], v17, off
	global_store_dword v[14:15], v18, off offset:64
	global_store_dword v[14:15], v19, off offset:128
	global_store_dword v[14:15], v20, off offset:192
	s_or_b64 exec, exec, s[22:23]
	ds_read_b32 v0, v217 offset:32
	v_mad_u64_u32 v[14:15], s[8:9], s86, 10, v[14:15]
	s_waitcnt lgkmcnt(0)
	v_rcp_f32_e32 v0, v0
	s_nop 0
	v_mul_f32_e32 v17, v84, v0
	v_mul_f32_e32 v18, v68, v0
	v_mul_f32_e32 v19, v52, v0
	v_mul_f32_e32 v20, v36, v0
	v_mov_b32_dpp v21, v17 quad_perm:[1,0,3,2] row_mask:0xf bank_mask:0xf bound_ctrl:1
	v_mov_b32_dpp v22, v18 quad_perm:[1,0,3,2] row_mask:0xf bank_mask:0xf bound_ctrl:1
	v_mov_b32_dpp v23, v19 quad_perm:[1,0,3,2] row_mask:0xf bank_mask:0xf bound_ctrl:1
	v_mov_b32_dpp v24, v20 quad_perm:[1,0,3,2] row_mask:0xf bank_mask:0xf bound_ctrl:1
	v_cvt_pk_bf16_f32 v17, v17, v21
	v_cvt_pk_bf16_f32 v18, v18, v22
	v_cvt_pk_bf16_f32 v19, v19, v23
	v_cvt_pk_bf16_f32 v20, v20, v24
	s_and_saveexec_b64 s[22:23], vcc
	global_store_dword v[14:15], v17, off
	global_store_dword v[14:15], v18, off offset:64
	global_store_dword v[14:15], v19, off offset:128
	global_store_dword v[14:15], v20, off offset:192
	s_or_b64 exec, exec, s[22:23]
	ds_read_b32 v0, v217 offset:36
	v_lshl_add_u64 v[14:15], v[14:15], 0, s[0:1]
	s_waitcnt lgkmcnt(0)
	v_rcp_f32_e32 v0, v0
	s_nop 0
	v_mul_f32_e32 v17, v85, v0
	v_mul_f32_e32 v18, v69, v0
	v_mul_f32_e32 v19, v53, v0
	v_mul_f32_e32 v20, v37, v0
	v_mov_b32_dpp v21, v17 quad_perm:[1,0,3,2] row_mask:0xf bank_mask:0xf bound_ctrl:1
	v_mov_b32_dpp v22, v18 quad_perm:[1,0,3,2] row_mask:0xf bank_mask:0xf bound_ctrl:1
	v_mov_b32_dpp v23, v19 quad_perm:[1,0,3,2] row_mask:0xf bank_mask:0xf bound_ctrl:1
	v_mov_b32_dpp v24, v20 quad_perm:[1,0,3,2] row_mask:0xf bank_mask:0xf bound_ctrl:1
	v_cvt_pk_bf16_f32 v17, v17, v21
	v_cvt_pk_bf16_f32 v18, v18, v22
	v_cvt_pk_bf16_f32 v19, v19, v23
	v_cvt_pk_bf16_f32 v20, v20, v24
	s_and_saveexec_b64 s[22:23], vcc
	global_store_dword v[14:15], v17, off
	global_store_dword v[14:15], v18, off offset:64
	global_store_dword v[14:15], v19, off offset:128
	global_store_dword v[14:15], v20, off offset:192
	s_or_b64 exec, exec, s[22:23]
	ds_read_b32 v0, v217 offset:40
	v_lshl_add_u64 v[14:15], v[14:15], 0, s[0:1]
	s_waitcnt lgkmcnt(0)
	v_rcp_f32_e32 v0, v0
	s_nop 0
	v_mul_f32_e32 v17, v86, v0
	v_mul_f32_e32 v18, v70, v0
	v_mul_f32_e32 v19, v54, v0
	v_mul_f32_e32 v20, v38, v0
	v_mov_b32_dpp v21, v17 quad_perm:[1,0,3,2] row_mask:0xf bank_mask:0xf bound_ctrl:1
	v_mov_b32_dpp v22, v18 quad_perm:[1,0,3,2] row_mask:0xf bank_mask:0xf bound_ctrl:1
	v_mov_b32_dpp v23, v19 quad_perm:[1,0,3,2] row_mask:0xf bank_mask:0xf bound_ctrl:1
	v_mov_b32_dpp v24, v20 quad_perm:[1,0,3,2] row_mask:0xf bank_mask:0xf bound_ctrl:1
	v_cvt_pk_bf16_f32 v17, v17, v21
	v_cvt_pk_bf16_f32 v18, v18, v22
	v_cvt_pk_bf16_f32 v19, v19, v23
	v_cvt_pk_bf16_f32 v20, v20, v24
	s_and_saveexec_b64 s[22:23], vcc
	global_store_dword v[14:15], v17, off
	global_store_dword v[14:15], v18, off offset:64
	global_store_dword v[14:15], v19, off offset:128
	global_store_dword v[14:15], v20, off offset:192
	s_or_b64 exec, exec, s[22:23]
	ds_read_b32 v0, v217 offset:44
	v_lshl_add_u64 v[14:15], v[14:15], 0, s[0:1]
	s_waitcnt lgkmcnt(0)
	v_rcp_f32_e32 v0, v0
	s_nop 0
	v_mul_f32_e32 v17, v87, v0
	v_mul_f32_e32 v18, v71, v0
	v_mul_f32_e32 v19, v55, v0
	v_mul_f32_e32 v20, v39, v0
	v_mov_b32_dpp v21, v17 quad_perm:[1,0,3,2] row_mask:0xf bank_mask:0xf bound_ctrl:1
	v_mov_b32_dpp v22, v18 quad_perm:[1,0,3,2] row_mask:0xf bank_mask:0xf bound_ctrl:1
	v_mov_b32_dpp v23, v19 quad_perm:[1,0,3,2] row_mask:0xf bank_mask:0xf bound_ctrl:1
	v_mov_b32_dpp v24, v20 quad_perm:[1,0,3,2] row_mask:0xf bank_mask:0xf bound_ctrl:1
	v_cvt_pk_bf16_f32 v17, v17, v21
	v_cvt_pk_bf16_f32 v18, v18, v22
	v_cvt_pk_bf16_f32 v19, v19, v23
	v_cvt_pk_bf16_f32 v20, v20, v24
	s_and_saveexec_b64 s[22:23], vcc
	global_store_dword v[14:15], v17, off
	global_store_dword v[14:15], v18, off offset:64
	global_store_dword v[14:15], v19, off offset:128
	global_store_dword v[14:15], v20, off offset:192
	s_or_b64 exec, exec, s[22:23]
	ds_read_b32 v0, v217 offset:64
	s_mul_hi_u32 s23, s86, 10
	s_mul_i32 s22, s86, 10
	v_lshl_add_u64 v[14:15], v[14:15], 0, s[22:23]
	s_waitcnt lgkmcnt(0)
	v_rcp_f32_e32 v0, v0
	s_nop 0
	v_mul_f32_e32 v17, v88, v0
	v_mul_f32_e32 v18, v72, v0
	v_mul_f32_e32 v19, v56, v0
	v_mul_f32_e32 v20, v40, v0
	v_mov_b32_dpp v21, v17 quad_perm:[1,0,3,2] row_mask:0xf bank_mask:0xf bound_ctrl:1
	v_mov_b32_dpp v22, v18 quad_perm:[1,0,3,2] row_mask:0xf bank_mask:0xf bound_ctrl:1
	v_mov_b32_dpp v23, v19 quad_perm:[1,0,3,2] row_mask:0xf bank_mask:0xf bound_ctrl:1
	v_mov_b32_dpp v24, v20 quad_perm:[1,0,3,2] row_mask:0xf bank_mask:0xf bound_ctrl:1
	v_cvt_pk_bf16_f32 v17, v17, v21
	v_cvt_pk_bf16_f32 v18, v18, v22
	v_cvt_pk_bf16_f32 v19, v19, v23
	v_cvt_pk_bf16_f32 v20, v20, v24
	s_and_saveexec_b64 s[24:25], vcc
	global_store_dword v[14:15], v17, off
	global_store_dword v[14:15], v18, off offset:64
	global_store_dword v[14:15], v19, off offset:128
	global_store_dword v[14:15], v20, off offset:192
	s_or_b64 exec, exec, s[24:25]
	ds_read_b32 v0, v217 offset:68
	v_lshl_add_u64 v[14:15], v[14:15], 0, s[0:1]
	s_waitcnt lgkmcnt(0)
	v_rcp_f32_e32 v0, v0
	s_nop 0
	v_mul_f32_e32 v17, v89, v0
	v_mul_f32_e32 v18, v73, v0
	v_mul_f32_e32 v19, v57, v0
	v_mul_f32_e32 v20, v41, v0
	v_mov_b32_dpp v21, v17 quad_perm:[1,0,3,2] row_mask:0xf bank_mask:0xf bound_ctrl:1
	v_mov_b32_dpp v22, v18 quad_perm:[1,0,3,2] row_mask:0xf bank_mask:0xf bound_ctrl:1
	v_mov_b32_dpp v23, v19 quad_perm:[1,0,3,2] row_mask:0xf bank_mask:0xf bound_ctrl:1
	v_mov_b32_dpp v24, v20 quad_perm:[1,0,3,2] row_mask:0xf bank_mask:0xf bound_ctrl:1
	v_cvt_pk_bf16_f32 v17, v17, v21
	v_cvt_pk_bf16_f32 v18, v18, v22
	v_cvt_pk_bf16_f32 v19, v19, v23
	v_cvt_pk_bf16_f32 v20, v20, v24
	s_and_saveexec_b64 s[24:25], vcc
	global_store_dword v[14:15], v17, off
	global_store_dword v[14:15], v18, off offset:64
	global_store_dword v[14:15], v19, off offset:128
	global_store_dword v[14:15], v20, off offset:192
	s_or_b64 exec, exec, s[24:25]
	ds_read_b32 v0, v217 offset:72
	v_lshl_add_u64 v[14:15], v[14:15], 0, s[0:1]
	s_waitcnt lgkmcnt(0)
	v_rcp_f32_e32 v0, v0
	s_nop 0
	v_mul_f32_e32 v17, v90, v0
	v_mul_f32_e32 v18, v74, v0
	v_mul_f32_e32 v19, v58, v0
	v_mul_f32_e32 v20, v42, v0
	v_mov_b32_dpp v21, v17 quad_perm:[1,0,3,2] row_mask:0xf bank_mask:0xf bound_ctrl:1
	v_mov_b32_dpp v22, v18 quad_perm:[1,0,3,2] row_mask:0xf bank_mask:0xf bound_ctrl:1
	v_mov_b32_dpp v23, v19 quad_perm:[1,0,3,2] row_mask:0xf bank_mask:0xf bound_ctrl:1
	v_mov_b32_dpp v24, v20 quad_perm:[1,0,3,2] row_mask:0xf bank_mask:0xf bound_ctrl:1
	v_cvt_pk_bf16_f32 v17, v17, v21
	v_cvt_pk_bf16_f32 v18, v18, v22
	v_cvt_pk_bf16_f32 v19, v19, v23
	v_cvt_pk_bf16_f32 v20, v20, v24
	s_and_saveexec_b64 s[24:25], vcc
	global_store_dword v[14:15], v17, off
	global_store_dword v[14:15], v18, off offset:64
	global_store_dword v[14:15], v19, off offset:128
	global_store_dword v[14:15], v20, off offset:192
	s_or_b64 exec, exec, s[24:25]
	ds_read_b32 v0, v217 offset:76
	v_lshl_add_u64 v[14:15], v[14:15], 0, s[0:1]
	s_waitcnt lgkmcnt(0)
	v_rcp_f32_e32 v0, v0
	s_nop 0
	v_mul_f32_e32 v17, v91, v0
	v_mul_f32_e32 v18, v75, v0
	v_mul_f32_e32 v19, v59, v0
	v_mul_f32_e32 v20, v43, v0
	v_mov_b32_dpp v21, v17 quad_perm:[1,0,3,2] row_mask:0xf bank_mask:0xf bound_ctrl:1
	v_mov_b32_dpp v22, v18 quad_perm:[1,0,3,2] row_mask:0xf bank_mask:0xf bound_ctrl:1
	v_mov_b32_dpp v23, v19 quad_perm:[1,0,3,2] row_mask:0xf bank_mask:0xf bound_ctrl:1
	v_mov_b32_dpp v24, v20 quad_perm:[1,0,3,2] row_mask:0xf bank_mask:0xf bound_ctrl:1
	v_cvt_pk_bf16_f32 v17, v17, v21
	v_cvt_pk_bf16_f32 v18, v18, v22
	v_cvt_pk_bf16_f32 v19, v19, v23
	v_cvt_pk_bf16_f32 v20, v20, v24
	s_and_saveexec_b64 s[24:25], vcc
	global_store_dword v[14:15], v17, off
	global_store_dword v[14:15], v18, off offset:64
	global_store_dword v[14:15], v19, off offset:128
	global_store_dword v[14:15], v20, off offset:192
	s_or_b64 exec, exec, s[24:25]
	ds_read_b32 v0, v217 offset:96
	v_lshl_add_u64 v[14:15], v[14:15], 0, s[22:23]
	s_waitcnt lgkmcnt(0)
	v_rcp_f32_e32 v0, v0
	s_nop 0
	v_mul_f32_e32 v17, v92, v0
	v_mul_f32_e32 v18, v76, v0
	v_mul_f32_e32 v19, v60, v0
	v_mul_f32_e32 v20, v44, v0
	v_mov_b32_dpp v21, v17 quad_perm:[1,0,3,2] row_mask:0xf bank_mask:0xf bound_ctrl:1
	v_mov_b32_dpp v22, v18 quad_perm:[1,0,3,2] row_mask:0xf bank_mask:0xf bound_ctrl:1
	v_mov_b32_dpp v23, v19 quad_perm:[1,0,3,2] row_mask:0xf bank_mask:0xf bound_ctrl:1
	v_mov_b32_dpp v24, v20 quad_perm:[1,0,3,2] row_mask:0xf bank_mask:0xf bound_ctrl:1
	v_cvt_pk_bf16_f32 v17, v17, v21
	v_cvt_pk_bf16_f32 v18, v18, v22
	v_cvt_pk_bf16_f32 v19, v19, v23
	v_cvt_pk_bf16_f32 v20, v20, v24
	s_and_saveexec_b64 s[22:23], vcc
	global_store_dword v[14:15], v17, off
	global_store_dword v[14:15], v18, off offset:64
	global_store_dword v[14:15], v19, off offset:128
	global_store_dword v[14:15], v20, off offset:192
	s_or_b64 exec, exec, s[22:23]
	ds_read_b32 v0, v217 offset:100
	v_lshl_add_u64 v[14:15], v[14:15], 0, s[0:1]
	s_waitcnt lgkmcnt(0)
	v_rcp_f32_e32 v0, v0
	s_nop 0
	v_mul_f32_e32 v17, v93, v0
	v_mul_f32_e32 v18, v77, v0
	v_mul_f32_e32 v19, v61, v0
	v_mul_f32_e32 v20, v45, v0
	v_mov_b32_dpp v21, v17 quad_perm:[1,0,3,2] row_mask:0xf bank_mask:0xf bound_ctrl:1
	v_mov_b32_dpp v22, v18 quad_perm:[1,0,3,2] row_mask:0xf bank_mask:0xf bound_ctrl:1
	v_mov_b32_dpp v23, v19 quad_perm:[1,0,3,2] row_mask:0xf bank_mask:0xf bound_ctrl:1
	v_mov_b32_dpp v24, v20 quad_perm:[1,0,3,2] row_mask:0xf bank_mask:0xf bound_ctrl:1
	v_cvt_pk_bf16_f32 v17, v17, v21
	v_cvt_pk_bf16_f32 v18, v18, v22
	v_cvt_pk_bf16_f32 v19, v19, v23
	v_cvt_pk_bf16_f32 v20, v20, v24
	s_and_saveexec_b64 s[22:23], vcc
	global_store_dword v[14:15], v17, off
	global_store_dword v[14:15], v18, off offset:64
	global_store_dword v[14:15], v19, off offset:128
	global_store_dword v[14:15], v20, off offset:192
	s_or_b64 exec, exec, s[22:23]
	ds_read_b32 v0, v217 offset:104
	v_lshl_add_u64 v[14:15], v[14:15], 0, s[0:1]
	s_waitcnt lgkmcnt(0)
	v_rcp_f32_e32 v0, v0
	s_nop 0
	v_mul_f32_e32 v17, v94, v0
	v_mul_f32_e32 v18, v78, v0
	v_mul_f32_e32 v19, v62, v0
	v_mul_f32_e32 v20, v46, v0
	v_mov_b32_dpp v21, v17 quad_perm:[1,0,3,2] row_mask:0xf bank_mask:0xf bound_ctrl:1
	v_mov_b32_dpp v22, v18 quad_perm:[1,0,3,2] row_mask:0xf bank_mask:0xf bound_ctrl:1
	v_mov_b32_dpp v23, v19 quad_perm:[1,0,3,2] row_mask:0xf bank_mask:0xf bound_ctrl:1
	v_mov_b32_dpp v24, v20 quad_perm:[1,0,3,2] row_mask:0xf bank_mask:0xf bound_ctrl:1
	v_cvt_pk_bf16_f32 v17, v17, v21
	v_cvt_pk_bf16_f32 v18, v18, v22
	v_cvt_pk_bf16_f32 v19, v19, v23
	v_cvt_pk_bf16_f32 v20, v20, v24
	s_and_saveexec_b64 s[22:23], vcc
	global_store_dword v[14:15], v17, off
	global_store_dword v[14:15], v18, off offset:64
	global_store_dword v[14:15], v19, off offset:128
	global_store_dword v[14:15], v20, off offset:192
	s_or_b64 exec, exec, s[22:23]
	ds_read_b32 v0, v217 offset:108
	v_lshl_add_u64 v[14:15], v[14:15], 0, s[0:1]
	s_waitcnt lgkmcnt(0)
	v_rcp_f32_e32 v0, v0
	s_nop 0
	v_mul_f32_e32 v17, v95, v0
	v_mul_f32_e32 v18, v79, v0
	v_mul_f32_e32 v19, v63, v0
	v_mul_f32_e32 v20, v47, v0
	v_mov_b32_dpp v21, v17 quad_perm:[1,0,3,2] row_mask:0xf bank_mask:0xf bound_ctrl:1
	v_mov_b32_dpp v22, v18 quad_perm:[1,0,3,2] row_mask:0xf bank_mask:0xf bound_ctrl:1
	v_mov_b32_dpp v23, v19 quad_perm:[1,0,3,2] row_mask:0xf bank_mask:0xf bound_ctrl:1
	v_mov_b32_dpp v24, v20 quad_perm:[1,0,3,2] row_mask:0xf bank_mask:0xf bound_ctrl:1
	v_cvt_pk_bf16_f32 v17, v17, v21
	v_cvt_pk_bf16_f32 v18, v18, v22
	v_cvt_pk_bf16_f32 v19, v19, v23
	v_cvt_pk_bf16_f32 v20, v20, v24
	s_and_saveexec_b64 s[0:1], vcc
	global_store_dword v[14:15], v17, off
	global_store_dword v[14:15], v18, off offset:64
	global_store_dword v[14:15], v19, off offset:128
	global_store_dword v[14:15], v20, off offset:192
	s_or_b64 exec, exec, s[0:1]
	s_branch .LBB0_505
